# phase 0 wave specialisation by order: waves 4-7 convert their x rows first (hand-written pass) then weights, waves 0-3 weights then x, so the bandwidth-bound and latency-bound streams overlap
# baseline (speedup 1.0000x reference)
; __device__ __forceinline__ int otid() { int t = threadIdx.x; asm volatile("" : "+v"(t)); return t; }
; #define PIN(i) karg_ptr(8 * (i))
; __global__ void __launch_bounds__(512, 2) fwd_megakernel(Params P) {
;     ...
;     if (EN(0) && IN(0)) {
;         { const int lane_ = otid() & 63, wv_ = otid() >> 6, gwv = bx * 8 + wv_, ngw = G * 8;
;     ...
;         for (int row0 = gw; row0 < MTOK; row0 += 4 * NGW) {
;             f32x4 xa[4][2][2];
; #pragma unroll
;             for (int k = 0; k < 4; ++k) { const int row = row0 + k * NGW; const float* xr = row < 16384 ? PIN(I_XP) + (size_t)row * DM : PIN(I_XS) + (size_t)(row - 16384) * DM;
; #pragma unroll
;                 for (int j = 0; j < 2; ++j) { xa[k][j][0] = *(const f32x4*)(xr + 8 * lane + 512 * j); xa[k][j][1] = *(const f32x4*)(xr + 8 * lane + 512 * j + 4); } }
; #pragma unroll
;             for (int k = 0; k < 4; ++k) { const int row = row0 + k * NGW; float s = 0.f;
; #pragma unroll
;                 for (int j = 0; j < 2; ++j) { const f32x4 a = xa[k][j][0], b = xa[k][j][1];
;                     s += (a[0] * a[0] + a[1] * a[1]) + (a[2] * a[2] + a[3] * a[3]) + (b[0] * b[0] + b[1] * b[1]) + (b[2] * b[2] + b[3] * b[3]);
;                     u32x4 o; o.x = pk2(a[0], a[1]); o.y = pk2(a[2], a[3]); o.z = pk2(b[0], b[1]); o.w = pk2(b[2], b[3]); *(u32x4*)(XB + (size_t)row * DM + 8 * lane + 512 * j) = o; }
;                 s = wave_sum(s); if (lane == 0) rstdA[row] = __builtin_amdgcn_rsqf(s * (1.0f / DM) + RMS_EPS); }
.LBB0_10:
	s_lshl_b32 s6, s2, 3
	v_writelane_b32 v255, s6, 4
	s_lshl_b32 s92, s3, 3
	s_andn2_b64 vcc, exec, s[4:5]
	s_mul_i32 s62, s3, 24
	s_cbranch_vccnz .LBB0_88
	v_lshrrev_b32_e32 v1, 6, v0
	s_nop 0
	v_readfirstlane_b32 s4, v1
	s_bitcmp1_b32 s4, 2
	s_cbranch_scc0 .Lp0_wfirst
	v_lshrrev_b32_e32 v22, 6, v0
	v_readlane_b32 s17, v255, 4
	s_load_dwordx2 s[4:5], s[0:1], 0x98
	s_load_dwordx2 s[8:9], s[0:1], 0x0
	s_load_dwordx2 s[10:11], s[0:1], 0x8
	v_readfirstlane_b32 s18, v22
	v_and_b32_e32 v22, 63, v0
	v_mov_b32_e32 v92, 0x358637bd
	s_add_i32 s17, s17, s18
	s_bfm_b64 s[12:13], 1, 63
	s_lshl_b32 s18, s17, 12
	v_lshl_add_u32 v18, v22, 5, s18
	s_lshl_b32 s18, s17, 11
	v_lshl_add_u32 v19, v22, 4, s18
	s_lshl_b32 s18, s17, 2
	v_mov_b32_e32 v20, s18
	s_waitcnt lgkmcnt(0)
	global_load_dwordx4 v[24:27], v18, s[8:9]
	global_load_dwordx4 v[28:31], v18, s[8:9] offset:16
	global_load_dwordx4 v[32:35], v18, s[8:9] offset:2048
	global_load_dwordx4 v[36:39], v18, s[8:9] offset:2064
	v_add_u32_e32 v18, 0x800000, v18
	global_load_dwordx4 v[40:43], v18, s[8:9]
	global_load_dwordx4 v[44:47], v18, s[8:9] offset:16
	global_load_dwordx4 v[48:51], v18, s[8:9] offset:2048
	global_load_dwordx4 v[52:55], v18, s[8:9] offset:2064
	v_add_u32_e32 v18, 0x800000, v18
	global_load_dwordx4 v[56:59], v18, s[8:9]
	global_load_dwordx4 v[60:63], v18, s[8:9] offset:16
	global_load_dwordx4 v[64:67], v18, s[8:9] offset:2048
	global_load_dwordx4 v[68:71], v18, s[8:9] offset:2064
	v_add_u32_e32 v18, 0x800000, v18
	global_load_dwordx4 v[72:75], v18, s[8:9]
	global_load_dwordx4 v[76:79], v18, s[8:9] offset:16
	global_load_dwordx4 v[80:83], v18, s[8:9] offset:2048
	global_load_dwordx4 v[84:87], v18, s[8:9] offset:2064
	s_waitcnt vmcnt(12)
	v_pk_mul_f32 v[88:89], v[24:25], v[24:25]
	v_pk_fma_f32 v[88:89], v[26:27], v[26:27], v[88:89]
	v_pk_fma_f32 v[88:89], v[28:29], v[28:29], v[88:89]
	v_pk_fma_f32 v[88:89], v[30:31], v[30:31], v[88:89]
	v_pk_fma_f32 v[88:89], v[32:33], v[32:33], v[88:89]
	v_pk_fma_f32 v[88:89], v[34:35], v[34:35], v[88:89]
	v_pk_fma_f32 v[88:89], v[36:37], v[36:37], v[88:89]
	v_pk_fma_f32 v[88:89], v[38:39], v[38:39], v[88:89]
	v_add_u32_e32 v19, 0x3001000, v19
	v_cvt_pk_bf16_f32 v24, v24, v25
	v_cvt_pk_bf16_f32 v25, v26, v27
	v_cvt_pk_bf16_f32 v26, v28, v29
	v_cvt_pk_bf16_f32 v27, v30, v31
	global_store_dwordx4 v19, v[24:27], s[4:5]
	v_cvt_pk_bf16_f32 v32, v32, v33
	v_cvt_pk_bf16_f32 v33, v34, v35
	v_cvt_pk_bf16_f32 v34, v36, v37
	v_cvt_pk_bf16_f32 v35, v38, v39
	global_store_dwordx4 v19, v[32:35], s[4:5] offset:1024
	v_add_f32_e32 v90, v88, v89
	v_add_u32_e32 v20, 0x2d00000, v20
	s_nop 1
	v_add_f32_dpp v90, v90, v90 quad_perm:[1,0,3,2] row_mask:0xf bank_mask:0xf
	s_nop 1
	v_add_f32_dpp v90, v90, v90 quad_perm:[2,3,0,1] row_mask:0xf bank_mask:0xf
	s_nop 1
	v_add_f32_dpp v90, v90, v90 row_half_mirror row_mask:0xf bank_mask:0xf
	s_nop 1
	v_add_f32_dpp v90, v90, v90 row_mirror row_mask:0xf bank_mask:0xf
	s_nop 1
	v_add_f32_dpp v90, v90, v90 row_bcast:15 row_mask:0xa bank_mask:0xf
	s_nop 1
	v_add_f32_dpp v90, v90, v90 row_bcast:31 row_mask:0xc bank_mask:0xf
	v_fmamk_f32 v91, v90, 0x3a800000, v92
	v_rsq_f32_e32 v91, v91
	s_mov_b64 exec, s[12:13]
	global_store_dword v20, v91, s[4:5]
	s_mov_b64 exec, -1
	v_add_u32_e32 v18, 0x800000, v18
	global_load_dwordx4 v[24:27], v18, s[8:9]
	global_load_dwordx4 v[28:31], v18, s[8:9] offset:16
	global_load_dwordx4 v[32:35], v18, s[8:9] offset:2048
	global_load_dwordx4 v[36:39], v18, s[8:9] offset:2064
	s_waitcnt vmcnt(15)
	v_pk_mul_f32 v[88:89], v[40:41], v[40:41]
	v_pk_fma_f32 v[88:89], v[42:43], v[42:43], v[88:89]
	v_pk_fma_f32 v[88:89], v[44:45], v[44:45], v[88:89]
	v_pk_fma_f32 v[88:89], v[46:47], v[46:47], v[88:89]
	v_pk_fma_f32 v[88:89], v[48:49], v[48:49], v[88:89]
	v_pk_fma_f32 v[88:89], v[50:51], v[50:51], v[88:89]
	v_pk_fma_f32 v[88:89], v[52:53], v[52:53], v[88:89]
	v_pk_fma_f32 v[88:89], v[54:55], v[54:55], v[88:89]
	v_add_u32_e32 v19, 0x400000, v19
	v_cvt_pk_bf16_f32 v40, v40, v41
	v_cvt_pk_bf16_f32 v41, v42, v43
	v_cvt_pk_bf16_f32 v42, v44, v45
	v_cvt_pk_bf16_f32 v43, v46, v47
	global_store_dwordx4 v19, v[40:43], s[4:5]
	v_cvt_pk_bf16_f32 v48, v48, v49
	v_cvt_pk_bf16_f32 v49, v50, v51
	v_cvt_pk_bf16_f32 v50, v52, v53
	v_cvt_pk_bf16_f32 v51, v54, v55
	global_store_dwordx4 v19, v[48:51], s[4:5] offset:1024
	v_add_f32_e32 v90, v88, v89
	v_add_u32_e32 v20, 0x2000, v20
	s_nop 1
	v_add_f32_dpp v90, v90, v90 quad_perm:[1,0,3,2] row_mask:0xf bank_mask:0xf
	s_nop 1
	v_add_f32_dpp v90, v90, v90 quad_perm:[2,3,0,1] row_mask:0xf bank_mask:0xf
	s_nop 1
	v_add_f32_dpp v90, v90, v90 row_half_mirror row_mask:0xf bank_mask:0xf
	s_nop 1
	v_add_f32_dpp v90, v90, v90 row_mirror row_mask:0xf bank_mask:0xf
	s_nop 1
	v_add_f32_dpp v90, v90, v90 row_bcast:15 row_mask:0xa bank_mask:0xf
	s_nop 1
	v_add_f32_dpp v90, v90, v90 row_bcast:31 row_mask:0xc bank_mask:0xf
	v_fmamk_f32 v91, v90, 0x3a800000, v92
	v_rsq_f32_e32 v91, v91
	s_mov_b64 exec, s[12:13]
	global_store_dword v20, v91, s[4:5]
	s_mov_b64 exec, -1
	v_add_u32_e32 v18, 0x800000, v18
	global_load_dwordx4 v[40:43], v18, s[8:9]
	global_load_dwordx4 v[44:47], v18, s[8:9] offset:16
	global_load_dwordx4 v[48:51], v18, s[8:9] offset:2048
	global_load_dwordx4 v[52:55], v18, s[8:9] offset:2064
	s_waitcnt vmcnt(18)
; #define PIN(i) karg_ptr(8 * (i))
; __global__ void __launch_bounds__(512, 2) fwd_megakernel(Params P) {
;     ...
;         for (int row0 = gw; row0 < MTOK; row0 += 4 * NGW) {
;             f32x4 xa[4][2][2];
; #pragma unroll
;             for (int k = 0; k < 4; ++k) { const int row = row0 + k * NGW; const float* xr = row < 16384 ? PIN(I_XP) + (size_t)row * DM : PIN(I_XS) + (size_t)(row - 16384) * DM;
; #pragma unroll
;                 for (int j = 0; j < 2; ++j) { xa[k][j][0] = *(const f32x4*)(xr + 8 * lane + 512 * j); xa[k][j][1] = *(const f32x4*)(xr + 8 * lane + 512 * j + 4); } }
; #pragma unroll
;             for (int k = 0; k < 4; ++k) { const int row = row0 + k * NGW; float s = 0.f;
; #pragma unroll
;                 for (int j = 0; j < 2; ++j) { const f32x4 a = xa[k][j][0], b = xa[k][j][1];
;                     s += (a[0] * a[0] + a[1] * a[1]) + (a[2] * a[2] + a[3] * a[3]) + (b[0] * b[0] + b[1] * b[1]) + (b[2] * b[2] + b[3] * b[3]);
;                     u32x4 o; o.x = pk2(a[0], a[1]); o.y = pk2(a[2], a[3]); o.z = pk2(b[0], b[1]); o.w = pk2(b[2], b[3]); *(u32x4*)(XB + (size_t)row * DM + 8 * lane + 512 * j) = o; }
;                 s = wave_sum(s); if (lane == 0) rstdA[row] = __builtin_amdgcn_rsqf(s * (1.0f / DM) + RMS_EPS); }
	v_pk_mul_f32 v[88:89], v[56:57], v[56:57]
	v_pk_fma_f32 v[88:89], v[58:59], v[58:59], v[88:89]
	v_pk_fma_f32 v[88:89], v[60:61], v[60:61], v[88:89]
	v_pk_fma_f32 v[88:89], v[62:63], v[62:63], v[88:89]
	v_pk_fma_f32 v[88:89], v[64:65], v[64:65], v[88:89]
	v_pk_fma_f32 v[88:89], v[66:67], v[66:67], v[88:89]
	v_pk_fma_f32 v[88:89], v[68:69], v[68:69], v[88:89]
	v_pk_fma_f32 v[88:89], v[70:71], v[70:71], v[88:89]
	v_add_u32_e32 v19, 0x400000, v19
	v_cvt_pk_bf16_f32 v56, v56, v57
	v_cvt_pk_bf16_f32 v57, v58, v59
	v_cvt_pk_bf16_f32 v58, v60, v61
	v_cvt_pk_bf16_f32 v59, v62, v63
	global_store_dwordx4 v19, v[56:59], s[4:5]
	v_cvt_pk_bf16_f32 v64, v64, v65
	v_cvt_pk_bf16_f32 v65, v66, v67
	v_cvt_pk_bf16_f32 v66, v68, v69
	v_cvt_pk_bf16_f32 v67, v70, v71
	global_store_dwordx4 v19, v[64:67], s[4:5] offset:1024
	v_add_f32_e32 v90, v88, v89
	v_add_u32_e32 v20, 0x2000, v20
	s_nop 1
	v_add_f32_dpp v90, v90, v90 quad_perm:[1,0,3,2] row_mask:0xf bank_mask:0xf
	s_nop 1
	v_add_f32_dpp v90, v90, v90 quad_perm:[2,3,0,1] row_mask:0xf bank_mask:0xf
	s_nop 1
	v_add_f32_dpp v90, v90, v90 row_half_mirror row_mask:0xf bank_mask:0xf
	s_nop 1
	v_add_f32_dpp v90, v90, v90 row_mirror row_mask:0xf bank_mask:0xf
	s_nop 1
	v_add_f32_dpp v90, v90, v90 row_bcast:15 row_mask:0xa bank_mask:0xf
	s_nop 1
	v_add_f32_dpp v90, v90, v90 row_bcast:31 row_mask:0xc bank_mask:0xf
	v_fmamk_f32 v91, v90, 0x3a800000, v92
	v_rsq_f32_e32 v91, v91
	s_mov_b64 exec, s[12:13]
	global_store_dword v20, v91, s[4:5]
	s_mov_b64 exec, -1
	v_add_u32_e32 v18, 0x800000, v18
	global_load_dwordx4 v[56:59], v18, s[8:9]
	global_load_dwordx4 v[60:63], v18, s[8:9] offset:16
	global_load_dwordx4 v[64:67], v18, s[8:9] offset:2048
	global_load_dwordx4 v[68:71], v18, s[8:9] offset:2064
	s_waitcnt vmcnt(21)
	v_pk_mul_f32 v[88:89], v[72:73], v[72:73]
	v_pk_fma_f32 v[88:89], v[74:75], v[74:75], v[88:89]
	v_pk_fma_f32 v[88:89], v[76:77], v[76:77], v[88:89]
	v_pk_fma_f32 v[88:89], v[78:79], v[78:79], v[88:89]
	v_pk_fma_f32 v[88:89], v[80:81], v[80:81], v[88:89]
	v_pk_fma_f32 v[88:89], v[82:83], v[82:83], v[88:89]
	v_pk_fma_f32 v[88:89], v[84:85], v[84:85], v[88:89]
	v_pk_fma_f32 v[88:89], v[86:87], v[86:87], v[88:89]
	v_add_u32_e32 v19, 0x400000, v19
	v_cvt_pk_bf16_f32 v72, v72, v73
	v_cvt_pk_bf16_f32 v73, v74, v75
	v_cvt_pk_bf16_f32 v74, v76, v77
	v_cvt_pk_bf16_f32 v75, v78, v79
	global_store_dwordx4 v19, v[72:75], s[4:5]
	v_cvt_pk_bf16_f32 v80, v80, v81
	v_cvt_pk_bf16_f32 v81, v82, v83
	v_cvt_pk_bf16_f32 v82, v84, v85
	v_cvt_pk_bf16_f32 v83, v86, v87
	global_store_dwordx4 v19, v[80:83], s[4:5] offset:1024
	v_add_f32_e32 v90, v88, v89
	v_add_u32_e32 v20, 0x2000, v20
	s_nop 1
	v_add_f32_dpp v90, v90, v90 quad_perm:[1,0,3,2] row_mask:0xf bank_mask:0xf
	s_nop 1
	v_add_f32_dpp v90, v90, v90 quad_perm:[2,3,0,1] row_mask:0xf bank_mask:0xf
	s_nop 1
	v_add_f32_dpp v90, v90, v90 row_half_mirror row_mask:0xf bank_mask:0xf
	s_nop 1
	v_add_f32_dpp v90, v90, v90 row_mirror row_mask:0xf bank_mask:0xf
	s_nop 1
	v_add_f32_dpp v90, v90, v90 row_bcast:15 row_mask:0xa bank_mask:0xf
	s_nop 1
	v_add_f32_dpp v90, v90, v90 row_bcast:31 row_mask:0xc bank_mask:0xf
	v_fmamk_f32 v91, v90, 0x3a800000, v92
	v_rsq_f32_e32 v91, v91
	s_mov_b64 exec, s[12:13]
	global_store_dword v20, v91, s[4:5]
	s_mov_b64 exec, -1
	v_add_u32_e32 v18, 0x800000, v18
	global_load_dwordx4 v[72:75], v18, s[8:9]
	global_load_dwordx4 v[76:79], v18, s[8:9] offset:16
	global_load_dwordx4 v[80:83], v18, s[8:9] offset:2048
	global_load_dwordx4 v[84:87], v18, s[8:9] offset:2064
	s_waitcnt vmcnt(21)
	v_pk_mul_f32 v[88:89], v[24:25], v[24:25]
	v_pk_fma_f32 v[88:89], v[26:27], v[26:27], v[88:89]
	v_pk_fma_f32 v[88:89], v[28:29], v[28:29], v[88:89]
	v_pk_fma_f32 v[88:89], v[30:31], v[30:31], v[88:89]
	v_pk_fma_f32 v[88:89], v[32:33], v[32:33], v[88:89]
	v_pk_fma_f32 v[88:89], v[34:35], v[34:35], v[88:89]
	v_pk_fma_f32 v[88:89], v[36:37], v[36:37], v[88:89]
	v_pk_fma_f32 v[88:89], v[38:39], v[38:39], v[88:89]
	v_add_u32_e32 v19, 0x400000, v19
	v_cvt_pk_bf16_f32 v24, v24, v25
	v_cvt_pk_bf16_f32 v25, v26, v27
	v_cvt_pk_bf16_f32 v26, v28, v29
	v_cvt_pk_bf16_f32 v27, v30, v31
	global_store_dwordx4 v19, v[24:27], s[4:5]
	v_cvt_pk_bf16_f32 v32, v32, v33
	v_cvt_pk_bf16_f32 v33, v34, v35
	v_cvt_pk_bf16_f32 v34, v36, v37
	v_cvt_pk_bf16_f32 v35, v38, v39
	global_store_dwordx4 v19, v[32:35], s[4:5] offset:1024
	v_add_f32_e32 v90, v88, v89
	v_add_u32_e32 v20, 0x2000, v20
	s_nop 1
	v_add_f32_dpp v90, v90, v90 quad_perm:[1,0,3,2] row_mask:0xf bank_mask:0xf
	s_nop 1
	v_add_f32_dpp v90, v90, v90 quad_perm:[2,3,0,1] row_mask:0xf bank_mask:0xf
	s_nop 1
	v_add_f32_dpp v90, v90, v90 row_half_mirror row_mask:0xf bank_mask:0xf
	s_nop 1
	v_add_f32_dpp v90, v90, v90 row_mirror row_mask:0xf bank_mask:0xf
	s_nop 1
	v_add_f32_dpp v90, v90, v90 row_bcast:15 row_mask:0xa bank_mask:0xf
	s_nop 1
	v_add_f32_dpp v90, v90, v90 row_bcast:31 row_mask:0xc bank_mask:0xf
	v_fmamk_f32 v91, v90, 0x3a800000, v92
	v_rsq_f32_e32 v91, v91
	s_mov_b64 exec, s[12:13]
	global_store_dword v20, v91, s[4:5]
	s_mov_b64 exec, -1
	v_add_u32_e32 v18, 0xfc800000, v18
	global_load_dwordx4 v[24:27], v18, s[10:11]
	global_load_dwordx4 v[28:31], v18, s[10:11] offset:16
	global_load_dwordx4 v[32:35], v18, s[10:11] offset:2048
	global_load_dwordx4 v[36:39], v18, s[10:11] offset:2064
	s_waitcnt vmcnt(21)
; #define PIN(i) karg_ptr(8 * (i))
; __global__ void __launch_bounds__(512, 2) fwd_megakernel(Params P) {
;     ...
;         for (int row0 = gw; row0 < MTOK; row0 += 4 * NGW) {
;             f32x4 xa[4][2][2];
; #pragma unroll
;             for (int k = 0; k < 4; ++k) { const int row = row0 + k * NGW; const float* xr = row < 16384 ? PIN(I_XP) + (size_t)row * DM : PIN(I_XS) + (size_t)(row - 16384) * DM;
; #pragma unroll
;                 for (int j = 0; j < 2; ++j) { xa[k][j][0] = *(const f32x4*)(xr + 8 * lane + 512 * j); xa[k][j][1] = *(const f32x4*)(xr + 8 * lane + 512 * j + 4); } }
; #pragma unroll
;             for (int k = 0; k < 4; ++k) { const int row = row0 + k * NGW; float s = 0.f;
; #pragma unroll
;                 for (int j = 0; j < 2; ++j) { const f32x4 a = xa[k][j][0], b = xa[k][j][1];
;                     s += (a[0] * a[0] + a[1] * a[1]) + (a[2] * a[2] + a[3] * a[3]) + (b[0] * b[0] + b[1] * b[1]) + (b[2] * b[2] + b[3] * b[3]);
;                     u32x4 o; o.x = pk2(a[0], a[1]); o.y = pk2(a[2], a[3]); o.z = pk2(b[0], b[1]); o.w = pk2(b[2], b[3]); *(u32x4*)(XB + (size_t)row * DM + 8 * lane + 512 * j) = o; }
;                 s = wave_sum(s); if (lane == 0) rstdA[row] = __builtin_amdgcn_rsqf(s * (1.0f / DM) + RMS_EPS); }
	v_pk_mul_f32 v[88:89], v[40:41], v[40:41]
	v_pk_fma_f32 v[88:89], v[42:43], v[42:43], v[88:89]
	v_pk_fma_f32 v[88:89], v[44:45], v[44:45], v[88:89]
	v_pk_fma_f32 v[88:89], v[46:47], v[46:47], v[88:89]
	v_pk_fma_f32 v[88:89], v[48:49], v[48:49], v[88:89]
	v_pk_fma_f32 v[88:89], v[50:51], v[50:51], v[88:89]
	v_pk_fma_f32 v[88:89], v[52:53], v[52:53], v[88:89]
	v_pk_fma_f32 v[88:89], v[54:55], v[54:55], v[88:89]
	v_add_u32_e32 v19, 0x400000, v19
	v_cvt_pk_bf16_f32 v40, v40, v41
	v_cvt_pk_bf16_f32 v41, v42, v43
	v_cvt_pk_bf16_f32 v42, v44, v45
	v_cvt_pk_bf16_f32 v43, v46, v47
	global_store_dwordx4 v19, v[40:43], s[4:5]
	v_cvt_pk_bf16_f32 v48, v48, v49
	v_cvt_pk_bf16_f32 v49, v50, v51
	v_cvt_pk_bf16_f32 v50, v52, v53
	v_cvt_pk_bf16_f32 v51, v54, v55
	global_store_dwordx4 v19, v[48:51], s[4:5] offset:1024
	v_add_f32_e32 v90, v88, v89
	v_add_u32_e32 v20, 0x2000, v20
	s_nop 1
	v_add_f32_dpp v90, v90, v90 quad_perm:[1,0,3,2] row_mask:0xf bank_mask:0xf
	s_nop 1
	v_add_f32_dpp v90, v90, v90 quad_perm:[2,3,0,1] row_mask:0xf bank_mask:0xf
	s_nop 1
	v_add_f32_dpp v90, v90, v90 row_half_mirror row_mask:0xf bank_mask:0xf
	s_nop 1
	v_add_f32_dpp v90, v90, v90 row_mirror row_mask:0xf bank_mask:0xf
	s_nop 1
	v_add_f32_dpp v90, v90, v90 row_bcast:15 row_mask:0xa bank_mask:0xf
	s_nop 1
	v_add_f32_dpp v90, v90, v90 row_bcast:31 row_mask:0xc bank_mask:0xf
	v_fmamk_f32 v91, v90, 0x3a800000, v92
	v_rsq_f32_e32 v91, v91
	s_mov_b64 exec, s[12:13]
	global_store_dword v20, v91, s[4:5]
	s_mov_b64 exec, -1
	v_add_u32_e32 v18, 0x800000, v18
	global_load_dwordx4 v[40:43], v18, s[10:11]
	global_load_dwordx4 v[44:47], v18, s[10:11] offset:16
	global_load_dwordx4 v[48:51], v18, s[10:11] offset:2048
	global_load_dwordx4 v[52:55], v18, s[10:11] offset:2064
	s_waitcnt vmcnt(21)
	v_pk_mul_f32 v[88:89], v[56:57], v[56:57]
	v_pk_fma_f32 v[88:89], v[58:59], v[58:59], v[88:89]
	v_pk_fma_f32 v[88:89], v[60:61], v[60:61], v[88:89]
	v_pk_fma_f32 v[88:89], v[62:63], v[62:63], v[88:89]
	v_pk_fma_f32 v[88:89], v[64:65], v[64:65], v[88:89]
	v_pk_fma_f32 v[88:89], v[66:67], v[66:67], v[88:89]
	v_pk_fma_f32 v[88:89], v[68:69], v[68:69], v[88:89]
	v_pk_fma_f32 v[88:89], v[70:71], v[70:71], v[88:89]
	v_add_u32_e32 v19, 0x400000, v19
	v_cvt_pk_bf16_f32 v56, v56, v57
	v_cvt_pk_bf16_f32 v57, v58, v59
	v_cvt_pk_bf16_f32 v58, v60, v61
	v_cvt_pk_bf16_f32 v59, v62, v63
	global_store_dwordx4 v19, v[56:59], s[4:5]
	v_cvt_pk_bf16_f32 v64, v64, v65
	v_cvt_pk_bf16_f32 v65, v66, v67
	v_cvt_pk_bf16_f32 v66, v68, v69
	v_cvt_pk_bf16_f32 v67, v70, v71
	global_store_dwordx4 v19, v[64:67], s[4:5] offset:1024
	v_add_f32_e32 v90, v88, v89
	v_add_u32_e32 v20, 0x2000, v20
	s_nop 1
	v_add_f32_dpp v90, v90, v90 quad_perm:[1,0,3,2] row_mask:0xf bank_mask:0xf
	s_nop 1
	v_add_f32_dpp v90, v90, v90 quad_perm:[2,3,0,1] row_mask:0xf bank_mask:0xf
	s_nop 1
	v_add_f32_dpp v90, v90, v90 row_half_mirror row_mask:0xf bank_mask:0xf
	s_nop 1
	v_add_f32_dpp v90, v90, v90 row_mirror row_mask:0xf bank_mask:0xf
	s_nop 1
	v_add_f32_dpp v90, v90, v90 row_bcast:15 row_mask:0xa bank_mask:0xf
	s_nop 1
	v_add_f32_dpp v90, v90, v90 row_bcast:31 row_mask:0xc bank_mask:0xf
	v_fmamk_f32 v91, v90, 0x3a800000, v92
	v_rsq_f32_e32 v91, v91
	s_mov_b64 exec, s[12:13]
	global_store_dword v20, v91, s[4:5]
	s_mov_b64 exec, -1
	v_add_u32_e32 v18, 0x800000, v18
	global_load_dwordx4 v[56:59], v18, s[10:11]
	global_load_dwordx4 v[60:63], v18, s[10:11] offset:16
	global_load_dwordx4 v[64:67], v18, s[10:11] offset:2048
	global_load_dwordx4 v[68:71], v18, s[10:11] offset:2064
	s_waitcnt vmcnt(21)
	v_pk_mul_f32 v[88:89], v[72:73], v[72:73]
	v_pk_fma_f32 v[88:89], v[74:75], v[74:75], v[88:89]
	v_pk_fma_f32 v[88:89], v[76:77], v[76:77], v[88:89]
	v_pk_fma_f32 v[88:89], v[78:79], v[78:79], v[88:89]
	v_pk_fma_f32 v[88:89], v[80:81], v[80:81], v[88:89]
	v_pk_fma_f32 v[88:89], v[82:83], v[82:83], v[88:89]
	v_pk_fma_f32 v[88:89], v[84:85], v[84:85], v[88:89]
	v_pk_fma_f32 v[88:89], v[86:87], v[86:87], v[88:89]
	v_add_u32_e32 v19, 0x400000, v19
	v_cvt_pk_bf16_f32 v72, v72, v73
	v_cvt_pk_bf16_f32 v73, v74, v75
	v_cvt_pk_bf16_f32 v74, v76, v77
	v_cvt_pk_bf16_f32 v75, v78, v79
	global_store_dwordx4 v19, v[72:75], s[4:5]
	v_cvt_pk_bf16_f32 v80, v80, v81
	v_cvt_pk_bf16_f32 v81, v82, v83
	v_cvt_pk_bf16_f32 v82, v84, v85
	v_cvt_pk_bf16_f32 v83, v86, v87
	global_store_dwordx4 v19, v[80:83], s[4:5] offset:1024
	v_add_f32_e32 v90, v88, v89
	v_add_u32_e32 v20, 0x2000, v20
	s_nop 1
	v_add_f32_dpp v90, v90, v90 quad_perm:[1,0,3,2] row_mask:0xf bank_mask:0xf
	s_nop 1
	v_add_f32_dpp v90, v90, v90 quad_perm:[2,3,0,1] row_mask:0xf bank_mask:0xf
	s_nop 1
	v_add_f32_dpp v90, v90, v90 row_half_mirror row_mask:0xf bank_mask:0xf
	s_nop 1
	v_add_f32_dpp v90, v90, v90 row_mirror row_mask:0xf bank_mask:0xf
	s_nop 1
	v_add_f32_dpp v90, v90, v90 row_bcast:15 row_mask:0xa bank_mask:0xf
	s_nop 1
	v_add_f32_dpp v90, v90, v90 row_bcast:31 row_mask:0xc bank_mask:0xf
	v_fmamk_f32 v91, v90, 0x3a800000, v92
	v_rsq_f32_e32 v91, v91
	s_mov_b64 exec, s[12:13]
	global_store_dword v20, v91, s[4:5]
	s_mov_b64 exec, -1
	v_add_u32_e32 v18, 0x800000, v18
	global_load_dwordx4 v[72:75], v18, s[10:11]
	global_load_dwordx4 v[76:79], v18, s[10:11] offset:16
	global_load_dwordx4 v[80:83], v18, s[10:11] offset:2048
	global_load_dwordx4 v[84:87], v18, s[10:11] offset:2064
	s_waitcnt vmcnt(21)
; #define PIN(i) karg_ptr(8 * (i))
; __global__ void __launch_bounds__(512, 2) fwd_megakernel(Params P) {
;     ...
;         for (int row0 = gw; row0 < MTOK; row0 += 4 * NGW) {
;             f32x4 xa[4][2][2];
; #pragma unroll
;             for (int k = 0; k < 4; ++k) { const int row = row0 + k * NGW; const float* xr = row < 16384 ? PIN(I_XP) + (size_t)row * DM : PIN(I_XS) + (size_t)(row - 16384) * DM;
; #pragma unroll
;                 for (int j = 0; j < 2; ++j) { xa[k][j][0] = *(const f32x4*)(xr + 8 * lane + 512 * j); xa[k][j][1] = *(const f32x4*)(xr + 8 * lane + 512 * j + 4); } }
; #pragma unroll
;             for (int k = 0; k < 4; ++k) { const int row = row0 + k * NGW; float s = 0.f;
; #pragma unroll
;                 for (int j = 0; j < 2; ++j) { const f32x4 a = xa[k][j][0], b = xa[k][j][1];
;                     s += (a[0] * a[0] + a[1] * a[1]) + (a[2] * a[2] + a[3] * a[3]) + (b[0] * b[0] + b[1] * b[1]) + (b[2] * b[2] + b[3] * b[3]);
;                     u32x4 o; o.x = pk2(a[0], a[1]); o.y = pk2(a[2], a[3]); o.z = pk2(b[0], b[1]); o.w = pk2(b[2], b[3]); *(u32x4*)(XB + (size_t)row * DM + 8 * lane + 512 * j) = o; }
;                 s = wave_sum(s); if (lane == 0) rstdA[row] = __builtin_amdgcn_rsqf(s * (1.0f / DM) + RMS_EPS); }
	v_pk_mul_f32 v[88:89], v[24:25], v[24:25]
	v_pk_fma_f32 v[88:89], v[26:27], v[26:27], v[88:89]
	v_pk_fma_f32 v[88:89], v[28:29], v[28:29], v[88:89]
	v_pk_fma_f32 v[88:89], v[30:31], v[30:31], v[88:89]
	v_pk_fma_f32 v[88:89], v[32:33], v[32:33], v[88:89]
	v_pk_fma_f32 v[88:89], v[34:35], v[34:35], v[88:89]
	v_pk_fma_f32 v[88:89], v[36:37], v[36:37], v[88:89]
	v_pk_fma_f32 v[88:89], v[38:39], v[38:39], v[88:89]
	v_add_u32_e32 v19, 0x400000, v19
	v_cvt_pk_bf16_f32 v24, v24, v25
	v_cvt_pk_bf16_f32 v25, v26, v27
	v_cvt_pk_bf16_f32 v26, v28, v29
	v_cvt_pk_bf16_f32 v27, v30, v31
	global_store_dwordx4 v19, v[24:27], s[4:5]
	v_cvt_pk_bf16_f32 v32, v32, v33
	v_cvt_pk_bf16_f32 v33, v34, v35
	v_cvt_pk_bf16_f32 v34, v36, v37
	v_cvt_pk_bf16_f32 v35, v38, v39
	global_store_dwordx4 v19, v[32:35], s[4:5] offset:1024
	v_add_f32_e32 v90, v88, v89
	v_add_u32_e32 v20, 0x2000, v20
	s_nop 1
	v_add_f32_dpp v90, v90, v90 quad_perm:[1,0,3,2] row_mask:0xf bank_mask:0xf
	s_nop 1
	v_add_f32_dpp v90, v90, v90 quad_perm:[2,3,0,1] row_mask:0xf bank_mask:0xf
	s_nop 1
	v_add_f32_dpp v90, v90, v90 row_half_mirror row_mask:0xf bank_mask:0xf
	s_nop 1
	v_add_f32_dpp v90, v90, v90 row_mirror row_mask:0xf bank_mask:0xf
	s_nop 1
	v_add_f32_dpp v90, v90, v90 row_bcast:15 row_mask:0xa bank_mask:0xf
	s_nop 1
	v_add_f32_dpp v90, v90, v90 row_bcast:31 row_mask:0xc bank_mask:0xf
	v_fmamk_f32 v91, v90, 0x3a800000, v92
	v_rsq_f32_e32 v91, v91
	s_mov_b64 exec, s[12:13]
	global_store_dword v20, v91, s[4:5]
	s_mov_b64 exec, -1
	v_add_u32_e32 v18, 0x800000, v18
	global_load_dwordx4 v[24:27], v18, s[10:11]
	global_load_dwordx4 v[28:31], v18, s[10:11] offset:16
	global_load_dwordx4 v[32:35], v18, s[10:11] offset:2048
	global_load_dwordx4 v[36:39], v18, s[10:11] offset:2064
	s_waitcnt vmcnt(21)
	v_pk_mul_f32 v[88:89], v[40:41], v[40:41]
	v_pk_fma_f32 v[88:89], v[42:43], v[42:43], v[88:89]
	v_pk_fma_f32 v[88:89], v[44:45], v[44:45], v[88:89]
	v_pk_fma_f32 v[88:89], v[46:47], v[46:47], v[88:89]
	v_pk_fma_f32 v[88:89], v[48:49], v[48:49], v[88:89]
	v_pk_fma_f32 v[88:89], v[50:51], v[50:51], v[88:89]
	v_pk_fma_f32 v[88:89], v[52:53], v[52:53], v[88:89]
	v_pk_fma_f32 v[88:89], v[54:55], v[54:55], v[88:89]
	v_add_u32_e32 v19, 0x400000, v19
	v_cvt_pk_bf16_f32 v40, v40, v41
	v_cvt_pk_bf16_f32 v41, v42, v43
	v_cvt_pk_bf16_f32 v42, v44, v45
	v_cvt_pk_bf16_f32 v43, v46, v47
	global_store_dwordx4 v19, v[40:43], s[4:5]
	v_cvt_pk_bf16_f32 v48, v48, v49
	v_cvt_pk_bf16_f32 v49, v50, v51
	v_cvt_pk_bf16_f32 v50, v52, v53
	v_cvt_pk_bf16_f32 v51, v54, v55
	global_store_dwordx4 v19, v[48:51], s[4:5] offset:1024
	v_add_f32_e32 v90, v88, v89
	v_add_u32_e32 v20, 0x2000, v20
	s_nop 1
	v_add_f32_dpp v90, v90, v90 quad_perm:[1,0,3,2] row_mask:0xf bank_mask:0xf
	s_nop 1
	v_add_f32_dpp v90, v90, v90 quad_perm:[2,3,0,1] row_mask:0xf bank_mask:0xf
	s_nop 1
	v_add_f32_dpp v90, v90, v90 row_half_mirror row_mask:0xf bank_mask:0xf
	s_nop 1
	v_add_f32_dpp v90, v90, v90 row_mirror row_mask:0xf bank_mask:0xf
	s_nop 1
	v_add_f32_dpp v90, v90, v90 row_bcast:15 row_mask:0xa bank_mask:0xf
	s_nop 1
	v_add_f32_dpp v90, v90, v90 row_bcast:31 row_mask:0xc bank_mask:0xf
	v_fmamk_f32 v91, v90, 0x3a800000, v92
	v_rsq_f32_e32 v91, v91
	s_mov_b64 exec, s[12:13]
	global_store_dword v20, v91, s[4:5]
	s_mov_b64 exec, -1
	v_add_u32_e32 v18, 0x800000, v18
	global_load_dwordx4 v[40:43], v18, s[10:11]
	global_load_dwordx4 v[44:47], v18, s[10:11] offset:16
	global_load_dwordx4 v[48:51], v18, s[10:11] offset:2048
	global_load_dwordx4 v[52:55], v18, s[10:11] offset:2064
	s_waitcnt vmcnt(21)
	v_pk_mul_f32 v[88:89], v[56:57], v[56:57]
	v_pk_fma_f32 v[88:89], v[58:59], v[58:59], v[88:89]
	v_pk_fma_f32 v[88:89], v[60:61], v[60:61], v[88:89]
	v_pk_fma_f32 v[88:89], v[62:63], v[62:63], v[88:89]
	v_pk_fma_f32 v[88:89], v[64:65], v[64:65], v[88:89]
	v_pk_fma_f32 v[88:89], v[66:67], v[66:67], v[88:89]
	v_pk_fma_f32 v[88:89], v[68:69], v[68:69], v[88:89]
	v_pk_fma_f32 v[88:89], v[70:71], v[70:71], v[88:89]
	v_add_u32_e32 v19, 0x400000, v19
	v_cvt_pk_bf16_f32 v56, v56, v57
	v_cvt_pk_bf16_f32 v57, v58, v59
	v_cvt_pk_bf16_f32 v58, v60, v61
	v_cvt_pk_bf16_f32 v59, v62, v63
	global_store_dwordx4 v19, v[56:59], s[4:5]
	v_cvt_pk_bf16_f32 v64, v64, v65
	v_cvt_pk_bf16_f32 v65, v66, v67
	v_cvt_pk_bf16_f32 v66, v68, v69
	v_cvt_pk_bf16_f32 v67, v70, v71
	global_store_dwordx4 v19, v[64:67], s[4:5] offset:1024
	v_add_f32_e32 v90, v88, v89
	v_add_u32_e32 v20, 0x2000, v20
	s_nop 1
	v_add_f32_dpp v90, v90, v90 quad_perm:[1,0,3,2] row_mask:0xf bank_mask:0xf
	s_nop 1
	v_add_f32_dpp v90, v90, v90 quad_perm:[2,3,0,1] row_mask:0xf bank_mask:0xf
	s_nop 1
	v_add_f32_dpp v90, v90, v90 row_half_mirror row_mask:0xf bank_mask:0xf
	s_nop 1
	v_add_f32_dpp v90, v90, v90 row_mirror row_mask:0xf bank_mask:0xf
	s_nop 1
	v_add_f32_dpp v90, v90, v90 row_bcast:15 row_mask:0xa bank_mask:0xf
	s_nop 1
	v_add_f32_dpp v90, v90, v90 row_bcast:31 row_mask:0xc bank_mask:0xf
	v_fmamk_f32 v91, v90, 0x3a800000, v92
	v_rsq_f32_e32 v91, v91
	s_mov_b64 exec, s[12:13]
	global_store_dword v20, v91, s[4:5]
	s_mov_b64 exec, -1
	v_add_u32_e32 v18, 0x800000, v18
	global_load_dwordx4 v[56:59], v18, s[10:11]
	global_load_dwordx4 v[60:63], v18, s[10:11] offset:16
	global_load_dwordx4 v[64:67], v18, s[10:11] offset:2048
	global_load_dwordx4 v[68:71], v18, s[10:11] offset:2064
	s_waitcnt vmcnt(21)
; #define PIN(i) karg_ptr(8 * (i))
; __global__ void __launch_bounds__(512, 2) fwd_megakernel(Params P) {
;     ...
;         for (int row0 = gw; row0 < MTOK; row0 += 4 * NGW) {
;             f32x4 xa[4][2][2];
; #pragma unroll
;             for (int k = 0; k < 4; ++k) { const int row = row0 + k * NGW; const float* xr = row < 16384 ? PIN(I_XP) + (size_t)row * DM : PIN(I_XS) + (size_t)(row - 16384) * DM;
; #pragma unroll
;                 for (int j = 0; j < 2; ++j) { xa[k][j][0] = *(const f32x4*)(xr + 8 * lane + 512 * j); xa[k][j][1] = *(const f32x4*)(xr + 8 * lane + 512 * j + 4); } }
; #pragma unroll
;             for (int k = 0; k < 4; ++k) { const int row = row0 + k * NGW; float s = 0.f;
; #pragma unroll
;                 for (int j = 0; j < 2; ++j) { const f32x4 a = xa[k][j][0], b = xa[k][j][1];
;                     s += (a[0] * a[0] + a[1] * a[1]) + (a[2] * a[2] + a[3] * a[3]) + (b[0] * b[0] + b[1] * b[1]) + (b[2] * b[2] + b[3] * b[3]);
;                     u32x4 o; o.x = pk2(a[0], a[1]); o.y = pk2(a[2], a[3]); o.z = pk2(b[0], b[1]); o.w = pk2(b[2], b[3]); *(u32x4*)(XB + (size_t)row * DM + 8 * lane + 512 * j) = o; }
;                 s = wave_sum(s); if (lane == 0) rstdA[row] = __builtin_amdgcn_rsqf(s * (1.0f / DM) + RMS_EPS); }
	v_pk_mul_f32 v[88:89], v[72:73], v[72:73]
	v_pk_fma_f32 v[88:89], v[74:75], v[74:75], v[88:89]
	v_pk_fma_f32 v[88:89], v[76:77], v[76:77], v[88:89]
	v_pk_fma_f32 v[88:89], v[78:79], v[78:79], v[88:89]
	v_pk_fma_f32 v[88:89], v[80:81], v[80:81], v[88:89]
	v_pk_fma_f32 v[88:89], v[82:83], v[82:83], v[88:89]
	v_pk_fma_f32 v[88:89], v[84:85], v[84:85], v[88:89]
	v_pk_fma_f32 v[88:89], v[86:87], v[86:87], v[88:89]
	v_add_u32_e32 v19, 0x400000, v19
	v_cvt_pk_bf16_f32 v72, v72, v73
	v_cvt_pk_bf16_f32 v73, v74, v75
	v_cvt_pk_bf16_f32 v74, v76, v77
	v_cvt_pk_bf16_f32 v75, v78, v79
	global_store_dwordx4 v19, v[72:75], s[4:5]
	v_cvt_pk_bf16_f32 v80, v80, v81
	v_cvt_pk_bf16_f32 v81, v82, v83
	v_cvt_pk_bf16_f32 v82, v84, v85
	v_cvt_pk_bf16_f32 v83, v86, v87
	global_store_dwordx4 v19, v[80:83], s[4:5] offset:1024
	v_add_f32_e32 v90, v88, v89
	v_add_u32_e32 v20, 0x2000, v20
	s_nop 1
	v_add_f32_dpp v90, v90, v90 quad_perm:[1,0,3,2] row_mask:0xf bank_mask:0xf
	s_nop 1
	v_add_f32_dpp v90, v90, v90 quad_perm:[2,3,0,1] row_mask:0xf bank_mask:0xf
	s_nop 1
	v_add_f32_dpp v90, v90, v90 row_half_mirror row_mask:0xf bank_mask:0xf
	s_nop 1
	v_add_f32_dpp v90, v90, v90 row_mirror row_mask:0xf bank_mask:0xf
	s_nop 1
	v_add_f32_dpp v90, v90, v90 row_bcast:15 row_mask:0xa bank_mask:0xf
	s_nop 1
	v_add_f32_dpp v90, v90, v90 row_bcast:31 row_mask:0xc bank_mask:0xf
	v_fmamk_f32 v91, v90, 0x3a800000, v92
	v_rsq_f32_e32 v91, v91
	s_mov_b64 exec, s[12:13]
	global_store_dword v20, v91, s[4:5]
	s_mov_b64 exec, -1
	v_add_u32_e32 v18, 0x800000, v18
	global_load_dwordx4 v[72:75], v18, s[10:11]
	global_load_dwordx4 v[76:79], v18, s[10:11] offset:16
	global_load_dwordx4 v[80:83], v18, s[10:11] offset:2048
	global_load_dwordx4 v[84:87], v18, s[10:11] offset:2064
	s_waitcnt vmcnt(21)
	v_pk_mul_f32 v[88:89], v[24:25], v[24:25]
	v_pk_fma_f32 v[88:89], v[26:27], v[26:27], v[88:89]
	v_pk_fma_f32 v[88:89], v[28:29], v[28:29], v[88:89]
	v_pk_fma_f32 v[88:89], v[30:31], v[30:31], v[88:89]
	v_pk_fma_f32 v[88:89], v[32:33], v[32:33], v[88:89]
	v_pk_fma_f32 v[88:89], v[34:35], v[34:35], v[88:89]
	v_pk_fma_f32 v[88:89], v[36:37], v[36:37], v[88:89]
	v_pk_fma_f32 v[88:89], v[38:39], v[38:39], v[88:89]
	v_add_u32_e32 v19, 0x400000, v19
	v_cvt_pk_bf16_f32 v24, v24, v25
	v_cvt_pk_bf16_f32 v25, v26, v27
	v_cvt_pk_bf16_f32 v26, v28, v29
	v_cvt_pk_bf16_f32 v27, v30, v31
	global_store_dwordx4 v19, v[24:27], s[4:5]
	v_cvt_pk_bf16_f32 v32, v32, v33
	v_cvt_pk_bf16_f32 v33, v34, v35
	v_cvt_pk_bf16_f32 v34, v36, v37
	v_cvt_pk_bf16_f32 v35, v38, v39
	global_store_dwordx4 v19, v[32:35], s[4:5] offset:1024
	v_add_f32_e32 v90, v88, v89
	v_add_u32_e32 v20, 0x2000, v20
	s_nop 1
	v_add_f32_dpp v90, v90, v90 quad_perm:[1,0,3,2] row_mask:0xf bank_mask:0xf
	s_nop 1
	v_add_f32_dpp v90, v90, v90 quad_perm:[2,3,0,1] row_mask:0xf bank_mask:0xf
	s_nop 1
	v_add_f32_dpp v90, v90, v90 row_half_mirror row_mask:0xf bank_mask:0xf
	s_nop 1
	v_add_f32_dpp v90, v90, v90 row_mirror row_mask:0xf bank_mask:0xf
	s_nop 1
	v_add_f32_dpp v90, v90, v90 row_bcast:15 row_mask:0xa bank_mask:0xf
	s_nop 1
	v_add_f32_dpp v90, v90, v90 row_bcast:31 row_mask:0xc bank_mask:0xf
	v_fmamk_f32 v91, v90, 0x3a800000, v92
	v_rsq_f32_e32 v91, v91
	s_mov_b64 exec, s[12:13]
	global_store_dword v20, v91, s[4:5]
	s_mov_b64 exec, -1
	s_waitcnt vmcnt(17)
	v_pk_mul_f32 v[88:89], v[40:41], v[40:41]
	v_pk_fma_f32 v[88:89], v[42:43], v[42:43], v[88:89]
	v_pk_fma_f32 v[88:89], v[44:45], v[44:45], v[88:89]
	v_pk_fma_f32 v[88:89], v[46:47], v[46:47], v[88:89]
	v_pk_fma_f32 v[88:89], v[48:49], v[48:49], v[88:89]
	v_pk_fma_f32 v[88:89], v[50:51], v[50:51], v[88:89]
	v_pk_fma_f32 v[88:89], v[52:53], v[52:53], v[88:89]
	v_pk_fma_f32 v[88:89], v[54:55], v[54:55], v[88:89]
	v_add_u32_e32 v19, 0x400000, v19
	v_cvt_pk_bf16_f32 v40, v40, v41
	v_cvt_pk_bf16_f32 v41, v42, v43
	v_cvt_pk_bf16_f32 v42, v44, v45
	v_cvt_pk_bf16_f32 v43, v46, v47
	global_store_dwordx4 v19, v[40:43], s[4:5]
	v_cvt_pk_bf16_f32 v48, v48, v49
	v_cvt_pk_bf16_f32 v49, v50, v51
	v_cvt_pk_bf16_f32 v50, v52, v53
	v_cvt_pk_bf16_f32 v51, v54, v55
	global_store_dwordx4 v19, v[48:51], s[4:5] offset:1024
	v_add_f32_e32 v90, v88, v89
	v_add_u32_e32 v20, 0x2000, v20
	s_nop 1
	v_add_f32_dpp v90, v90, v90 quad_perm:[1,0,3,2] row_mask:0xf bank_mask:0xf
	s_nop 1
	v_add_f32_dpp v90, v90, v90 quad_perm:[2,3,0,1] row_mask:0xf bank_mask:0xf
	s_nop 1
	v_add_f32_dpp v90, v90, v90 row_half_mirror row_mask:0xf bank_mask:0xf
	s_nop 1
	v_add_f32_dpp v90, v90, v90 row_mirror row_mask:0xf bank_mask:0xf
	s_nop 1
	v_add_f32_dpp v90, v90, v90 row_bcast:15 row_mask:0xa bank_mask:0xf
	s_nop 1
	v_add_f32_dpp v90, v90, v90 row_bcast:31 row_mask:0xc bank_mask:0xf
	v_fmamk_f32 v91, v90, 0x3a800000, v92
	v_rsq_f32_e32 v91, v91
	s_mov_b64 exec, s[12:13]
	global_store_dword v20, v91, s[4:5]
	s_mov_b64 exec, -1
	s_waitcnt vmcnt(13)
; #define LAS __attribute__((address_space(3)))
; #define PIN(i) karg_ptr(8 * (i))
; __global__ void __launch_bounds__(512, 2) fwd_megakernel(Params P) {
;     ...
;         { const int lane_ = otid() & 63, wv_ = otid() >> 6, gwv = bx * 8 + wv_, ngw = G * 8;
;           LAS float* scr = (LAS float*)lds + wv_ * (64 * 33);
;           auto rid = [](int n) { return n; };
;           for (int l = 0; l < NLAYER; ++l) {
;             const float lam_init = 0.8f - 0.6f * expf(-0.3f * (float)l);
;             {
;                 const float* W = PIN(I_WIN) + (size_t)l * DM * NZ; const float* gpre = PIN(I_LNMPRE) + l * DM; bf16_t* WT = (bf16_t*)(ws + OFF_WIN + l * SZ_WIN);
;                 auto src = [=](int k, int n) { return W[(size_t)k * NZ + n] * gpre[k] * (n < 512 ? QSCALE : 1.0f); };
;                 for (int it = gwv; it < 16 * 64; it += ngw) tconv_item(scr, WT, DM, (it >> 6) * 64, (it & 63) * 32, lane_, src, rid);
;             }
;             {
;                 const float* W = PIN(I_WOUT) + (size_t)l * DM * DM; const float* hn = PIN(I_HNORM) + l * 128; bf16_t* WT = (bf16_t*)(ws + OFF_WOUT + l * SZ_WOUT); const float hs = 1.0f - lam_init;
;                 auto src = [=](int k, int n) { return W[(size_t)k * DM + n] * hn[k & 127] * hs; };
;     ...
;         for (int row0 = gw; row0 < MTOK; row0 += 4 * NGW) {
;             f32x4 xa[4][2][2];
; #pragma unroll
;             for (int k = 0; k < 4; ++k) { const int row = row0 + k * NGW; const float* xr = row < 16384 ? PIN(I_XP) + (size_t)row * DM : PIN(I_XS) + (size_t)(row - 16384) * DM;
; #pragma unroll
;                 for (int j = 0; j < 2; ++j) { xa[k][j][0] = *(const f32x4*)(xr + 8 * lane + 512 * j); xa[k][j][1] = *(const f32x4*)(xr + 8 * lane + 512 * j + 4); } }
; #pragma unroll
;             for (int k = 0; k < 4; ++k) { const int row = row0 + k * NGW; float s = 0.f;
; #pragma unroll
;                 for (int j = 0; j < 2; ++j) { const f32x4 a = xa[k][j][0], b = xa[k][j][1];
;                     s += (a[0] * a[0] + a[1] * a[1]) + (a[2] * a[2] + a[3] * a[3]) + (b[0] * b[0] + b[1] * b[1]) + (b[2] * b[2] + b[3] * b[3]);
;                     u32x4 o; o.x = pk2(a[0], a[1]); o.y = pk2(a[2], a[3]); o.z = pk2(b[0], b[1]); o.w = pk2(b[2], b[3]); *(u32x4*)(XB + (size_t)row * DM + 8 * lane + 512 * j) = o; }
;                 s = wave_sum(s); if (lane == 0) rstdA[row] = __builtin_amdgcn_rsqf(s * (1.0f / DM) + RMS_EPS); }
	v_pk_mul_f32 v[88:89], v[56:57], v[56:57]
	v_pk_fma_f32 v[88:89], v[58:59], v[58:59], v[88:89]
	v_pk_fma_f32 v[88:89], v[60:61], v[60:61], v[88:89]
	v_pk_fma_f32 v[88:89], v[62:63], v[62:63], v[88:89]
	v_pk_fma_f32 v[88:89], v[64:65], v[64:65], v[88:89]
	v_pk_fma_f32 v[88:89], v[66:67], v[66:67], v[88:89]
	v_pk_fma_f32 v[88:89], v[68:69], v[68:69], v[88:89]
	v_pk_fma_f32 v[88:89], v[70:71], v[70:71], v[88:89]
	v_add_u32_e32 v19, 0x400000, v19
	v_cvt_pk_bf16_f32 v56, v56, v57
	v_cvt_pk_bf16_f32 v57, v58, v59
	v_cvt_pk_bf16_f32 v58, v60, v61
	v_cvt_pk_bf16_f32 v59, v62, v63
	global_store_dwordx4 v19, v[56:59], s[4:5]
	v_cvt_pk_bf16_f32 v64, v64, v65
	v_cvt_pk_bf16_f32 v65, v66, v67
	v_cvt_pk_bf16_f32 v66, v68, v69
	v_cvt_pk_bf16_f32 v67, v70, v71
	global_store_dwordx4 v19, v[64:67], s[4:5] offset:1024
	v_add_f32_e32 v90, v88, v89
	v_add_u32_e32 v20, 0x2000, v20
	s_nop 1
	v_add_f32_dpp v90, v90, v90 quad_perm:[1,0,3,2] row_mask:0xf bank_mask:0xf
	s_nop 1
	v_add_f32_dpp v90, v90, v90 quad_perm:[2,3,0,1] row_mask:0xf bank_mask:0xf
	s_nop 1
	v_add_f32_dpp v90, v90, v90 row_half_mirror row_mask:0xf bank_mask:0xf
	s_nop 1
	v_add_f32_dpp v90, v90, v90 row_mirror row_mask:0xf bank_mask:0xf
	s_nop 1
	v_add_f32_dpp v90, v90, v90 row_bcast:15 row_mask:0xa bank_mask:0xf
	s_nop 1
	v_add_f32_dpp v90, v90, v90 row_bcast:31 row_mask:0xc bank_mask:0xf
	v_fmamk_f32 v91, v90, 0x3a800000, v92
	v_rsq_f32_e32 v91, v91
	s_mov_b64 exec, s[12:13]
	global_store_dword v20, v91, s[4:5]
	s_mov_b64 exec, -1
	s_waitcnt vmcnt(9)
	v_pk_mul_f32 v[88:89], v[72:73], v[72:73]
	v_pk_fma_f32 v[88:89], v[74:75], v[74:75], v[88:89]
	v_pk_fma_f32 v[88:89], v[76:77], v[76:77], v[88:89]
	v_pk_fma_f32 v[88:89], v[78:79], v[78:79], v[88:89]
	v_pk_fma_f32 v[88:89], v[80:81], v[80:81], v[88:89]
	v_pk_fma_f32 v[88:89], v[82:83], v[82:83], v[88:89]
	v_pk_fma_f32 v[88:89], v[84:85], v[84:85], v[88:89]
	v_pk_fma_f32 v[88:89], v[86:87], v[86:87], v[88:89]
	v_add_u32_e32 v19, 0x400000, v19
	v_cvt_pk_bf16_f32 v72, v72, v73
	v_cvt_pk_bf16_f32 v73, v74, v75
	v_cvt_pk_bf16_f32 v74, v76, v77
	v_cvt_pk_bf16_f32 v75, v78, v79
	global_store_dwordx4 v19, v[72:75], s[4:5]
	v_cvt_pk_bf16_f32 v80, v80, v81
	v_cvt_pk_bf16_f32 v81, v82, v83
	v_cvt_pk_bf16_f32 v82, v84, v85
	v_cvt_pk_bf16_f32 v83, v86, v87
	global_store_dwordx4 v19, v[80:83], s[4:5] offset:1024
	v_add_f32_e32 v90, v88, v89
	v_add_u32_e32 v20, 0x2000, v20
	s_nop 1
	v_add_f32_dpp v90, v90, v90 quad_perm:[1,0,3,2] row_mask:0xf bank_mask:0xf
	s_nop 1
	v_add_f32_dpp v90, v90, v90 quad_perm:[2,3,0,1] row_mask:0xf bank_mask:0xf
	s_nop 1
	v_add_f32_dpp v90, v90, v90 row_half_mirror row_mask:0xf bank_mask:0xf
	s_nop 1
	v_add_f32_dpp v90, v90, v90 row_mirror row_mask:0xf bank_mask:0xf
	s_nop 1
	v_add_f32_dpp v90, v90, v90 row_bcast:15 row_mask:0xa bank_mask:0xf
	s_nop 1
	v_add_f32_dpp v90, v90, v90 row_bcast:31 row_mask:0xc bank_mask:0xf
	v_fmamk_f32 v91, v90, 0x3a800000, v92
	v_rsq_f32_e32 v91, v91
	s_mov_b64 exec, s[12:13]
	global_store_dword v20, v91, s[4:5]
	s_mov_b64 exec, -1
.Lp0_wfirst:
	v_mov_b32_e32 v1, v0
	v_mov_b32_e32 v2, v0
	v_readlane_b32 s4, v255, 4
	v_ashrrev_i32_e32 v3, 6, v2
	v_bfe_u32 v18, v1, 5, 1
	v_add_u32_e32 v19, s4, v3
	s_movk_i32 s4, 0x2100
	v_mul_lo_u32 v2, v3, s4
	v_and_b32_e32 v20, 31, v1
	v_bfe_u32 v21, v1, 3, 3
	v_lshlrev_b32_e32 v1, 3, v1
	v_add_u32_e32 v4, 0, v2
	v_and_b32_e32 v2, 56, v1
	v_lshlrev_b32_e32 v5, 2, v20
	v_mul_u32_u24_e32 v1, 0x84, v2
	v_lshlrev_b32_e32 v6, 2, v21
	s_mov_b32 s17, 0
	s_movk_i32 s4, 0x400
	v_add_u32_e32 v22, v4, v5
	v_mov_b32_e32 v25, 0
	v_add3_u32 v23, v4, v1, v6
	s_movk_i32 s6, 0x100
	s_movk_i32 s31, 0x200
	v_lshlrev_b32_e32 v26, 2, v18
	s_movk_i32 s10, 0xb00
	s_movk_i32 s12, 0x580
	v_lshlrev_b32_e32 v4, 12, v18
	s_mov_b32 s16, 0xe000
	v_lshlrev_b32_e32 v3, 5, v3
	s_mov_b32 s94, s62
	v_cmp_gt_i32_e64 s[4:5], s4, v19
	s_movk_i32 s30, 0x84
	v_or_b32_e32 v48, 8, v21
	v_or_b32_e32 v49, 16, v21
	v_or_b32_e32 v50, 24, v21
	v_cmp_gt_i32_e64 s[6:7], s6, v19
	v_cmp_gt_i32_e64 s[8:9], s31, v19
	v_mov_b32_e32 v27, v25
	v_cmp_gt_i32_e64 s[10:11], s10, v19
	v_cmp_gt_i32_e64 s[12:13], s12, v19
	v_mov_b32_e32 v1, v18
	v_or3_b32 v28, v4, v5, s16
	v_mov_b32_e32 v29, v25
	v_lshl_add_u32 v51, s2, 8, v3
	s_lshl_b32 s33, s3, 8
	s_mov_b64 s[36:37], -1
	s_movk_i32 s38, 0x3ff
	s_mov_b32 s39, 0x3fb8aa3b
	s_mov_b32 s40, 0xc2ce8ed0
	s_mov_b32 s41, 0x42b17218
	v_mov_b32_e32 v52, 0xbf4ccccd
	s_mov_b64 s[18:19], 0x800000
	s_movk_i32 s52, 0x3e0
	s_movk_i32 s53, 0xff
	s_movk_i32 s54, 0xf80
	s_movk_i32 s55, 0x60
	s_mov_b32 s56, 0xffff2000
	s_mov_b32 s57, 0xffff4000
	s_mov_b32 s58, 0xffff6000
	s_movk_i32 s59, 0x8000
	s_movk_i32 s60, 0xa000
	s_movk_i32 s61, 0xc000
	s_movk_i32 s62, 0xe000
	s_mov_b64 s[20:21], 0x10000
	v_lshlrev_b32_e32 v30, 1, v26
	s_mov_b64 s[22:23], 0x800400
	s_mov_b32 s63, 0x800000
	s_movk_i32 s64, 0x1ff
	s_mov_b64 s[24:25], 0xc00000
	s_mov_b32 s65, 0x2e8ba2e9
	s_movk_i32 s66, 0xb0
	s_movk_i32 s67, 0x5800
	s_movk_i32 s68, 0xaff
	s_movk_i32 s69, 0x80
	s_movk_i32 s70, 0xff00
	s_mov_b64 s[26:27], 0x2200000
	s_movk_i32 s71, 0x57f
	v_lshlrev_b32_e32 v32, 1, v2
	v_mov_b32_e32 v53, 0x3e38aa3b
	v_mov_b32_e32 v54, 0x7f800000
	s_mov_b32 s16, s17
	s_branch .LBB0_13

; #define PIN(i) karg_ptr(8 * (i))
; __global__ void __launch_bounds__(512, 2) fwd_megakernel(Params P) {
;     ...
;         for (int row0 = gw; row0 < MTOK; row0 += 4 * NGW) {
;             f32x4 xa[4][2][2];
; #pragma unroll
;             for (int k = 0; k < 4; ++k) { const int row = row0 + k * NGW; const float* xr = row < 16384 ? PIN(I_XP) + (size_t)row * DM : PIN(I_XS) + (size_t)(row - 16384) * DM;
; #pragma unroll
;                 for (int j = 0; j < 2; ++j) { xa[k][j][0] = *(const f32x4*)(xr + 8 * lane + 512 * j); xa[k][j][1] = *(const f32x4*)(xr + 8 * lane + 512 * j + 4); } }
.LBB0_54:
	v_lshrrev_b32_e32 v1, 6, v0
	v_readlane_b32 s4, v255, 4
	s_nop 1
	v_add_u32_e32 v66, s4, v1
	s_mov_b32 s4, 0x8000
	v_cmp_gt_i32_e32 vcc, s4, v66
	s_and_saveexec_b64 s[6:7], vcc
	s_mov_b32 s62, s94
	v_readfirstlane_b32 s4, v1
	s_bitcmp1_b32 s4, 2
	s_cbranch_scc1 .LBB0_81
	s_cbranch_execz .LBB0_81
	v_and_b32_e32 v1, 63, v0
	v_ashrrev_i32_e32 v67, 31, v66
	v_mov_b64_e32 v[2:3], 0x2d00000
	v_lshlrev_b32_e32 v68, 3, v1
	s_lshl_b32 s10, s3, 5
	v_lshl_add_u64 v[72:73], v[66:67], 2, v[2:3]
	v_lshlrev_b64 v[2:3], 11, v[66:67]
	s_mov_b32 s9, 0
	v_mov_b32_e32 v71, 0
	v_cmp_eq_u32_e64 s[4:5], 0, v1
	s_ashr_i32 s11, s10, 31
	v_lshl_or_b32 v2, v1, 4, v2
	s_mov_b64 s[16:17], 0x3001400
	v_lshlrev_b32_e32 v76, 2, v68
	v_mbcnt_lo_u32_b32 v1, -1, 0
	s_lshl_b64 s[12:13], s[10:11], 2
	v_lshl_add_u64 v[74:75], v[2:3], 0, s[16:17]
	s_lshl_b64 s[16:17], s[10:11], 11
	s_lshl_b32 s8, s3, 4
	s_mov_b32 s63, s9
	s_mov_b32 s93, s9
	s_ashr_i32 s19, s92, 31
	s_mov_b32 s18, s92
	s_mov_b64 s[20:21], 0
	s_movk_i32 s26, 0x3fff
	v_mov_b32_e32 v78, v76
	v_mov_b32_e32 v79, v71
	v_mbcnt_hi_u32_b32 v1, -1, v1
	v_mov_b32_e32 v69, 0x358637bd
	s_mov_b32 s27, 0x3001000
	s_movk_i32 s28, 0x7fff
	s_branch .LBB0_57
